# same as previous (h1 recomputed in phase 10) but x pointers kept in spare lanes of the spill VGPR instead of extra SGPRs
# speedup vs baseline: 1.0432x; 1.0004x over previous
.LBB0_77:
	s_lshl_b32 s2, s47, 3
	s_mov_b32 s0, s2
	s_waitcnt vmcnt(0)
	v_lshrrev_b32_e32 v9, 6, v49
	v_writelane_b32 v252, s0, 40
	s_lshl_b32 s50, s46, 3
	v_writelane_b32 v252, s1, 41
	v_mbcnt_lo_u32_b32 v209, -1, 0
	v_and_b32_e32 v10, 63, v49
	v_readlane_b32 s16, v252, 14
	v_readlane_b32 s17, v252, 15
	v_readlane_b32 s18, v252, 18
	v_readlane_b32 s19, v252, 19
	v_readfirstlane_b32 s3, v9
	v_lshlrev_b32_e32 v0, 4, v10
	v_lshlrev_b32_e32 v1, 3, v10
	v_add_u32_e32 v124, 0x1000, v0
	v_lshlrev_b32_e32 v11, 2, v10
	v_xor_b32_e32 v2, 0x80, v11
	v_xor_b32_e32 v3, 64, v11
	v_xor_b32_e32 v4, 32, v11
	v_xor_b32_e32 v5, 16, v11
	v_xor_b32_e32 v6, 8, v11
	v_xor_b32_e32 v7, 4, v11
	v_mov_b32_e32 v8, 0x358637bd
	v_mov_b32_e32 v122, 0
	v_mov_b32_e32 v123, 0
	s_add_i32 s2, s2, s3
	s_mov_b32 s3, s50
	s_mov_b32 s10, 0
	s_mov_b64 s[76:77], s[16:17]
	s_waitcnt lgkmcnt(0)
	v_writelane_b32 v252, s60, 60
	v_writelane_b32 v252, s61, 61
	v_writelane_b32 v252, s62, 62
	v_writelane_b32 v252, s63, 63
	global_load_dwordx4 v[12:15], v0, s[76:77]
	global_load_dwordx4 v[16:19], v0, s[76:77] offset:1024
	global_load_dwordx4 v[20:23], v0, s[76:77] offset:2048
	global_load_dwordx4 v[24:27], v0, s[76:77] offset:3072
	global_load_dwordx4 v[28:31], v124, s[76:77]
	global_load_dwordx4 v[32:35], v124, s[76:77] offset:1024
	global_load_dwordx4 v[36:39], v124, s[76:77] offset:2048
	global_load_dwordx4 v[40:43], v124, s[76:77] offset:3072

.LBB0_1462:
	s_or_b64 exec, exec, s[0:1]
	s_waitcnt lgkmcnt(0)
	s_barrier
	v_and_b32_e32 v3, 63, v208
	v_lshrrev_b32_e32 v4, 6, v208
	v_readlane_b32 s18, v252, 16
	v_readlane_b32 s19, v252, 17
	v_readlane_b32 s22, v252, 2
	v_readlane_b32 s23, v252, 3
	v_readlane_b32 s30, v252, 60
	v_readlane_b32 s31, v252, 61
	v_readlane_b32 s34, v252, 62
	v_readlane_b32 s35, v252, 63
	v_lshlrev_b32_e32 v0, 4, v3
	v_readfirstlane_b32 s2, v4
	v_lshlrev_b32_e32 v1, 5, v3
	v_lshlrev_b32_e32 v4, 2, v3
	v_add_u32_e32 v2, 0x1000, v1
	v_xor_b32_e32 v5, 0x80, v4
	v_xor_b32_e32 v6, 64, v4
	v_xor_b32_e32 v7, 32, v4
	v_xor_b32_e32 v8, 16, v4
	v_xor_b32_e32 v9, 8, v4
	v_xor_b32_e32 v10, 4, v4
	v_mov_b32_e32 v11, 0x358637bd
	s_add_i32 s2, s2, s74
	s_mov_b32 s3, s50
	s_add_u32 s20, s18, 0x2000
	s_addc_u32 s21, s19, 0
	s_add_u32 s24, s96, 0x20cc0000
	s_addc_u32 s25, s97, 0
	s_add_u32 s26, s96, 0x1d300000
	s_addc_u32 s27, s97, 0
	s_cmp_ge_u32 s2, 0x2080
	s_cbranch_scc1 .Lp10_done
	global_load_dwordx4 v[12:15], v1, s[18:19]
	global_load_dwordx4 v[16:19], v1, s[18:19] offset:16
	global_load_dwordx4 v[20:23], v1, s[18:19] offset:2048
	global_load_dwordx4 v[24:27], v1, s[18:19] offset:2064
	global_load_dwordx4 v[28:31], v2, s[18:19]
	global_load_dwordx4 v[32:35], v2, s[18:19] offset:16
	global_load_dwordx4 v[36:39], v2, s[18:19] offset:2048
	global_load_dwordx4 v[40:43], v2, s[18:19] offset:2064
	global_load_dwordx4 v[44:47], v1, s[20:21]
	global_load_dwordx4 v[48:51], v1, s[20:21] offset:16
	global_load_dwordx4 v[52:55], v1, s[20:21] offset:2048
	global_load_dwordx4 v[56:59], v1, s[20:21] offset:2064
	global_load_dwordx4 v[60:63], v2, s[20:21]
	global_load_dwordx4 v[64:67], v2, s[20:21] offset:16
	global_load_dwordx4 v[68:71], v2, s[20:21] offset:2048
	global_load_dwordx4 v[72:75], v2, s[20:21] offset:2064
	s_lshl_b32 s4, s2, 12
	s_add_u32 s6, s24, s4
	s_addc_u32 s7, s25, 0
	s_add_u32 s16, s26, s4
	s_addc_u32 s17, s27, 0
	s_lshl_b32 s4, s2, 13
	s_cmp_lt_u32 s2, 0x2000
	s_cselect_b32 s8, s30, s34
	s_cselect_b32 s9, s31, s35
	s_cselect_b32 s28, 0, 0x4000000
	s_sub_u32 s4, s4, s28
	s_add_u32 s8, s8, s4
	s_addc_u32 s9, s9, 0
	global_load_dwordx4 v[76:79], v0, s[6:7]
	global_load_dwordx4 v[80:83], v0, s[6:7] offset:1024
	global_load_dwordx4 v[84:87], v0, s[6:7] offset:2048
	global_load_dwordx4 v[88:91], v0, s[6:7] offset:3072
	global_load_dwordx4 v[92:95], v0, s[16:17]
	global_load_dwordx4 v[96:99], v0, s[16:17] offset:1024
	global_load_dwordx4 v[100:103], v0, s[16:17] offset:2048
	global_load_dwordx4 v[104:107], v0, s[16:17] offset:3072
	global_load_dwordx4 v[108:111], v1, s[8:9]
	global_load_dwordx4 v[112:115], v1, s[8:9] offset:16
	global_load_dwordx4 v[116:119], v1, s[8:9] offset:2048
	global_load_dwordx4 v[120:123], v1, s[8:9] offset:2064
	global_load_dwordx4 v[124:127], v2, s[8:9]
	global_load_dwordx4 v[128:131], v2, s[8:9] offset:16
	global_load_dwordx4 v[132:135], v2, s[8:9] offset:2048
	global_load_dwordx4 v[136:139], v2, s[8:9] offset:2064
	s_waitcnt vmcnt(0)
	s_branch .Lp10_A_go

.Lp10_A_go:
	s_add_u32 s29, s2, s3
	s_cmp_ge_u32 s29, 0x2080
	s_cbranch_scc1 .Lp10_A_nopf
	s_lshl_b32 s4, s29, 12
	s_add_u32 s6, s24, s4
	s_addc_u32 s7, s25, 0
	s_add_u32 s16, s26, s4
	s_addc_u32 s17, s27, 0
	s_lshl_b32 s4, s29, 13
	s_cmp_lt_u32 s29, 0x2000
	s_cselect_b32 s8, s30, s34
	s_cselect_b32 s9, s31, s35
	s_cselect_b32 s28, 0, 0x4000000
	s_sub_u32 s4, s4, s28
	s_add_u32 s8, s8, s4
	s_addc_u32 s9, s9, 0
	global_load_dwordx4 v[140:143], v0, s[6:7]
	global_load_dwordx4 v[144:147], v0, s[6:7] offset:1024
	global_load_dwordx4 v[148:151], v0, s[6:7] offset:2048
	global_load_dwordx4 v[152:155], v0, s[6:7] offset:3072
	global_load_dwordx4 v[156:159], v0, s[16:17]
	global_load_dwordx4 v[160:163], v0, s[16:17] offset:1024
	global_load_dwordx4 v[164:167], v0, s[16:17] offset:2048
	global_load_dwordx4 v[168:171], v0, s[16:17] offset:3072
	global_load_dwordx4 v[172:175], v1, s[8:9]
	global_load_dwordx4 v[176:179], v1, s[8:9] offset:16
	global_load_dwordx4 v[180:183], v1, s[8:9] offset:2048
	global_load_dwordx4 v[184:187], v1, s[8:9] offset:2064
	global_load_dwordx4 v[188:191], v2, s[8:9]
	global_load_dwordx4 v[192:195], v2, s[8:9] offset:16
	global_load_dwordx4 v[196:199], v2, s[8:9] offset:2048
	global_load_dwordx4 v[200:203], v2, s[8:9] offset:2064

.Lp10_B:
	s_waitcnt vmcnt(8)
	s_add_u32 s29, s2, s3
	s_cmp_ge_u32 s29, 0x2080
	s_cbranch_scc1 .Lp10_B_nopf
	s_lshl_b32 s4, s29, 12
	s_add_u32 s6, s24, s4
	s_addc_u32 s7, s25, 0
	s_add_u32 s16, s26, s4
	s_addc_u32 s17, s27, 0
	s_lshl_b32 s4, s29, 13
	s_cmp_lt_u32 s29, 0x2000
	s_cselect_b32 s8, s30, s34
	s_cselect_b32 s9, s31, s35
	s_cselect_b32 s28, 0, 0x4000000
	s_sub_u32 s4, s4, s28
	s_add_u32 s8, s8, s4
	s_addc_u32 s9, s9, 0
	global_load_dwordx4 v[76:79], v0, s[6:7]
	global_load_dwordx4 v[80:83], v0, s[6:7] offset:1024
	global_load_dwordx4 v[84:87], v0, s[6:7] offset:2048
	global_load_dwordx4 v[88:91], v0, s[6:7] offset:3072
	global_load_dwordx4 v[92:95], v0, s[16:17]
	global_load_dwordx4 v[96:99], v0, s[16:17] offset:1024
	global_load_dwordx4 v[100:103], v0, s[16:17] offset:2048
	global_load_dwordx4 v[104:107], v0, s[16:17] offset:3072
	global_load_dwordx4 v[108:111], v1, s[8:9]
	global_load_dwordx4 v[112:115], v1, s[8:9] offset:16
	global_load_dwordx4 v[116:119], v1, s[8:9] offset:2048
	global_load_dwordx4 v[120:123], v1, s[8:9] offset:2064
	global_load_dwordx4 v[124:127], v2, s[8:9]
	global_load_dwordx4 v[128:131], v2, s[8:9] offset:16
	global_load_dwordx4 v[132:135], v2, s[8:9] offset:2048
	global_load_dwordx4 v[136:139], v2, s[8:9] offset:2064
